# gate (gelu branch) stores marked nt: read three phases later, keep urec/xc resident
# baseline (speedup 1.0000x reference)
; __device__ __forceinline__ float gelu_tanh_f(float x) { const float z = 0.7978845608028654f * (x + 0.044715f * x * x * x); return x * sigmoid_f(2.0f * z); }
; __device__ __forceinline__ u32x4 pack8(const f32x4 a, const f32x4 b) { u32x4 w; w.x = cvt_pk_rtz(a[0], a[1]); w.y = cvt_pk_rtz(a[2], a[3]); w.z = cvt_pk_rtz(b[0], b[1]); w.w = cvt_pk_rtz(b[2], b[3]); return w; }
; template <class T> __device__ __forceinline__ T* at(const void* base, unsigned byteoff) { return (T*)((char*)base + byteoff); }
;     __device__ __forceinline__ void operator()(const Acc& acc, const pg8::Unit& u, int wr, int wc, int fr, int fq, LAS float* rcache, int& cached_pm) const {
;     ...
;         if (pn < 4) {
;             bf16_t* base = gate + pn * 256;
; #pragma unroll
;             for (int ai = 0; ai < 2; ++ai)
; #pragma unroll
;                 for (int m = 0; m < 4; ++m) {
;                     const int row = row0 + ai * 128 + m * 16; const float rs = rs8[ai * 4 + m];
; #pragma unroll
;                     for (int bj = 0; bj < 2; ++bj) {
;                         f32x4 v0 = acc[ai][bj][m][0] * rs, v1 = acc[ai][bj][m][1] * rs;
; #pragma unroll
;                         for (int j = 0; j < 4; ++j) { v0[j] = gelu_tanh_f(v0[j]); v1[j] = gelu_tanh_f(v1[j]); }
;                         *at<u32x4>(base, (unsigned)(row * DM + bj * 128 + cl) * 2u) = pack8(v0, v1);
;                     }
;                 }
.LBB0_183:
	s_andn2_b64 vcc, exec, s[60:61]
	s_cbranch_vccnz .LBB0_185
	v_mul_f32_e32 v131, 0x3d372713, v122
	v_mul_f32_e32 v131, v122, v131
	v_fma_f32 v131, v122, v131, v122
	v_mul_f32_e32 v131, 0x3f4c422a, v131
	v_add_f32_e32 v131, v131, v131
	v_mul_f32_e32 v131, 0xbfb8aa3b, v131
	v_exp_f32_e32 v131, v131
	v_mul_f32_e32 v130, 0x3d372713, v126
	v_mul_f32_e32 v130, v126, v130
	v_fma_f32 v130, v126, v130, v126
	v_add_f32_e32 v131, 1.0, v131
	v_rcp_f32_e32 v132, v131
	v_mul_f32_e32 v131, 0x3d372713, v127
	v_mul_f32_e32 v131, v127, v131
	v_fma_f32 v131, v127, v131, v127
	v_mul_f32_e32 v130, 0x3f4c422a, v130
	v_mul_f32_e32 v131, 0x3f4c422a, v131
	v_add_f32_e32 v130, v130, v130
	v_add_f32_e32 v131, v131, v131
	v_mul_f32_e32 v130, 0xbfb8aa3b, v130
	v_mul_f32_e32 v131, 0xbfb8aa3b, v131
	v_exp_f32_e32 v130, v130
	v_exp_f32_e32 v131, v131
	v_pk_mul_f32 v[124:125], v[124:125], v[160:161] op_sel_hi:[1,0]
	v_pk_mul_f32 v[128:129], v[128:129], v[160:161] op_sel_hi:[1,0]
	v_add_f32_e32 v130, 1.0, v130
	v_add_f32_e32 v131, 1.0, v131
	v_rcp_f32_e32 v130, v130
	v_rcp_f32_e32 v131, v131
	s_ashr_i32 s29, s28, 31
	s_lshl_b64 s[22:23], s[28:29], 1
	s_add_u32 s40, s44, s22
	v_pk_mul_f32 v[126:127], v[126:127], v[130:131]
	v_mul_f32_e32 v130, 0x3d372713, v123
	v_mul_f32_e32 v130, v123, v130
	v_fma_f32 v130, v123, v130, v123
	v_mul_f32_e32 v130, 0x3f4c422a, v130
	v_add_f32_e32 v130, v130, v130
	v_mul_f32_e32 v130, 0xbfb8aa3b, v130
	v_exp_f32_e32 v130, v130
	s_addc_u32 s41, s45, s23
	v_pk_mul_f32 v[116:117], v[116:117], v[160:161] op_sel_hi:[1,0]
	v_pk_mul_f32 v[120:121], v[120:121], v[160:161] op_sel_hi:[1,0]
	v_add_f32_e32 v130, 1.0, v130
	v_rcp_f32_e32 v133, v130
	v_pk_mul_f32 v[108:109], v[108:109], v[160:161] op_sel:[0,1]
	v_pk_mul_f32 v[112:113], v[112:113], v[160:161] op_sel:[0,1]
	v_pk_mul_f32 v[100:101], v[100:101], v[160:161] op_sel:[0,1]
	v_pk_mul_f32 v[130:131], v[122:123], v[132:133]
	v_mul_f32_e32 v123, 0x3d372713, v124
	v_mul_f32_e32 v123, v124, v123
	v_fma_f32 v123, v124, v123, v124
	v_mul_f32_e32 v123, 0x3f4c422a, v123
	v_add_f32_e32 v123, v123, v123
	v_mul_f32_e32 v123, 0xbfb8aa3b, v123
	v_exp_f32_e32 v123, v123
	v_mul_f32_e32 v122, 0x3d372713, v128
	v_mul_f32_e32 v122, v128, v122
	v_fma_f32 v122, v128, v122, v128
	v_add_f32_e32 v123, 1.0, v123
	v_rcp_f32_e32 v132, v123
	v_mul_f32_e32 v123, 0x3d372713, v129
	v_mul_f32_e32 v123, v129, v123
	v_fma_f32 v123, v129, v123, v129
	v_mul_f32_e32 v122, 0x3f4c422a, v122
	v_mul_f32_e32 v123, 0x3f4c422a, v123
	v_add_f32_e32 v122, v122, v122
	v_add_f32_e32 v123, v123, v123
	v_mul_f32_e32 v122, 0xbfb8aa3b, v122
	v_mul_f32_e32 v123, 0xbfb8aa3b, v123
	v_exp_f32_e32 v122, v122
	v_exp_f32_e32 v123, v123
	v_pk_mul_f32 v[104:105], v[104:105], v[160:161] op_sel:[0,1]
	v_pk_mul_f32 v[90:91], v[90:91], v[158:159] op_sel_hi:[1,0]
	v_add_f32_e32 v122, 1.0, v122
	v_add_f32_e32 v123, 1.0, v123
	v_rcp_f32_e32 v122, v122
	v_rcp_f32_e32 v123, v123
	v_pk_mul_f32 v[94:95], v[94:95], v[158:159] op_sel_hi:[1,0]
	v_pk_mul_f32 v[92:93], v[92:93], v[158:159] op_sel_hi:[1,0]
	v_pk_mul_f32 v[96:97], v[96:97], v[158:159] op_sel_hi:[1,0]
	v_pk_mul_f32 v[128:129], v[128:129], v[122:123]
	v_mul_f32_e32 v122, 0x3d372713, v125
	v_mul_f32_e32 v122, v125, v122
	v_fma_f32 v122, v125, v122, v125
	v_mul_f32_e32 v122, 0x3f4c422a, v122
	v_add_f32_e32 v122, v122, v122
	v_mul_f32_e32 v122, 0xbfb8aa3b, v122
	v_exp_f32_e32 v122, v122
	v_cvt_pk_bf16_f32 v123, v128, v129
	v_pk_mul_f32 v[82:83], v[82:83], v[158:159] op_sel_hi:[1,0]
	v_pk_mul_f32 v[86:87], v[86:87], v[158:159] op_sel_hi:[1,0]
	v_add_f32_e32 v122, 1.0, v122
	v_rcp_f32_e32 v133, v122
	v_cvt_pk_bf16_f32 v122, v126, v127
	v_pk_mul_f32 v[84:85], v[84:85], v[158:159] op_sel_hi:[1,0]
	v_pk_mul_f32 v[88:89], v[88:89], v[158:159] op_sel_hi:[1,0]
	v_pk_mul_f32 v[132:133], v[124:125], v[132:133]
	v_cvt_pk_bf16_f32 v124, v130, v131
	v_cvt_pk_bf16_f32 v125, v132, v133
	global_store_dwordx4 v140, v[122:125], s[40:41] nt
	v_pk_mul_f32 v[56:57], v[56:57], v[138:139] op_sel_hi:[1,0]
	v_pk_mul_f32 v[60:61], v[60:61], v[138:139] op_sel_hi:[1,0]
	v_mul_f32_e32 v123, 0x3d372713, v114
	v_mul_f32_e32 v123, v114, v123
	v_fma_f32 v123, v114, v123, v114
	v_mul_f32_e32 v123, 0x3f4c422a, v123
	v_add_f32_e32 v123, v123, v123
	v_mul_f32_e32 v123, 0xbfb8aa3b, v123
	v_exp_f32_e32 v123, v123
	v_mul_f32_e32 v122, 0x3d372713, v118
	v_mul_f32_e32 v122, v118, v122
	v_fma_f32 v122, v118, v122, v118
	v_add_f32_e32 v123, 1.0, v123
	v_rcp_f32_e32 v124, v123
	v_mul_f32_e32 v123, 0x3d372713, v119
	v_mul_f32_e32 v123, v119, v123
	v_fma_f32 v123, v119, v123, v119
	v_mul_f32_e32 v122, 0x3f4c422a, v122
	v_mul_f32_e32 v123, 0x3f4c422a, v123
	v_add_f32_e32 v122, v122, v122
	v_add_f32_e32 v123, v123, v123
	v_mul_f32_e32 v122, 0xbfb8aa3b, v122
	v_mul_f32_e32 v123, 0xbfb8aa3b, v123
	v_exp_f32_e32 v122, v122
	v_exp_f32_e32 v123, v123
	v_pk_mul_f32 v[58:59], v[58:59], v[138:139] op_sel_hi:[1,0]
	v_pk_mul_f32 v[62:63], v[62:63], v[138:139] op_sel_hi:[1,0]
	v_add_f32_e32 v122, 1.0, v122
	v_add_f32_e32 v123, 1.0, v123
	v_rcp_f32_e32 v122, v122
	v_rcp_f32_e32 v123, v123
	v_pk_mul_f32 v[48:49], v[48:49], v[138:139] op_sel_hi:[1,0]
	v_pk_mul_f32 v[52:53], v[52:53], v[138:139] op_sel_hi:[1,0]
	v_pk_mul_f32 v[50:51], v[50:51], v[138:139] op_sel_hi:[1,0]
	v_pk_mul_f32 v[118:119], v[118:119], v[122:123]
	v_mul_f32_e32 v122, 0x3d372713, v115
	v_mul_f32_e32 v122, v115, v122
	v_fma_f32 v122, v115, v122, v115
	v_mul_f32_e32 v122, 0x3f4c422a, v122
	v_add_f32_e32 v122, v122, v122
	v_mul_f32_e32 v122, 0xbfb8aa3b, v122
	v_exp_f32_e32 v122, v122
	v_pk_mul_f32 v[54:55], v[54:55], v[138:139] op_sel_hi:[1,0]
	v_pk_mul_f32 v[24:25], v[24:25], v[134:135] op_sel_hi:[1,0]
; __device__ __forceinline__ float gelu_tanh_f(float x) { const float z = 0.7978845608028654f * (x + 0.044715f * x * x * x); return x * sigmoid_f(2.0f * z); }
; __device__ __forceinline__ u32x4 pack8(const f32x4 a, const f32x4 b) { u32x4 w; w.x = cvt_pk_rtz(a[0], a[1]); w.y = cvt_pk_rtz(a[2], a[3]); w.z = cvt_pk_rtz(b[0], b[1]); w.w = cvt_pk_rtz(b[2], b[3]); return w; }
; template <class T> __device__ __forceinline__ T* at(const void* base, unsigned byteoff) { return (T*)((char*)base + byteoff); }
;     __device__ __forceinline__ void operator()(const Acc& acc, const pg8::Unit& u, int wr, int wc, int fr, int fq, LAS float* rcache, int& cached_pm) const {
;     ...
;         if (pn < 4) {
;             bf16_t* base = gate + pn * 256;
; #pragma unroll
;             for (int ai = 0; ai < 2; ++ai)
; #pragma unroll
;                 for (int m = 0; m < 4; ++m) {
;                     const int row = row0 + ai * 128 + m * 16; const float rs = rs8[ai * 4 + m];
; #pragma unroll
;                     for (int bj = 0; bj < 2; ++bj) {
;                         f32x4 v0 = acc[ai][bj][m][0] * rs, v1 = acc[ai][bj][m][1] * rs;
; #pragma unroll
;                         for (int j = 0; j < 4; ++j) { v0[j] = gelu_tanh_f(v0[j]); v1[j] = gelu_tanh_f(v1[j]); }
;                         *at<u32x4>(base, (unsigned)(row * DM + bj * 128 + cl) * 2u) = pack8(v0, v1);
;                     }
;                 }
	v_pk_mul_f32 v[28:29], v[28:29], v[134:135] op_sel_hi:[1,0]
	v_add_f32_e32 v122, 1.0, v122
	v_rcp_f32_e32 v125, v122
	v_pk_mul_f32 v[26:27], v[26:27], v[134:135] op_sel_hi:[1,0]
	v_pk_mul_f32 v[30:31], v[30:31], v[134:135] op_sel_hi:[1,0]
	v_pk_mul_f32 v[16:17], v[16:17], v[134:135] op_sel_hi:[1,0]
	v_pk_mul_f32 v[122:123], v[114:115], v[124:125]
	v_mul_f32_e32 v115, 0x3d372713, v116
	v_mul_f32_e32 v115, v116, v115
	v_fma_f32 v115, v116, v115, v116
	v_mul_f32_e32 v115, 0x3f4c422a, v115
	v_add_f32_e32 v115, v115, v115
	v_mul_f32_e32 v115, 0xbfb8aa3b, v115
	v_exp_f32_e32 v115, v115
	v_mul_f32_e32 v114, 0x3d372713, v120
	v_mul_f32_e32 v114, v120, v114
	v_fma_f32 v114, v120, v114, v120
	v_add_f32_e32 v115, 1.0, v115
	v_rcp_f32_e32 v124, v115
	v_mul_f32_e32 v115, 0x3d372713, v121
	v_mul_f32_e32 v115, v121, v115
	v_fma_f32 v115, v121, v115, v121
	v_mul_f32_e32 v114, 0x3f4c422a, v114
	v_mul_f32_e32 v115, 0x3f4c422a, v115
	v_add_f32_e32 v114, v114, v114
	v_add_f32_e32 v115, v115, v115
	v_mul_f32_e32 v114, 0xbfb8aa3b, v114
	v_mul_f32_e32 v115, 0xbfb8aa3b, v115
	v_exp_f32_e32 v114, v114
	v_exp_f32_e32 v115, v115
	v_pk_mul_f32 v[20:21], v[20:21], v[134:135] op_sel_hi:[1,0]
	v_pk_mul_f32 v[18:19], v[18:19], v[134:135] op_sel_hi:[1,0]
	v_add_f32_e32 v114, 1.0, v114
	v_add_f32_e32 v115, 1.0, v115
	v_rcp_f32_e32 v114, v114
	v_rcp_f32_e32 v115, v115
	v_pk_mul_f32 v[22:23], v[22:23], v[134:135] op_sel_hi:[1,0]
	v_mov_b32_e32 v141, v140
	v_pk_mul_f32 v[120:121], v[120:121], v[114:115]
	v_mul_f32_e32 v114, 0x3d372713, v117
	v_mul_f32_e32 v114, v117, v114
	v_fma_f32 v114, v117, v114, v117
	v_mul_f32_e32 v114, 0x3f4c422a, v114
	v_add_f32_e32 v114, v114, v114
	v_mul_f32_e32 v114, 0xbfb8aa3b, v114
	v_exp_f32_e32 v114, v114
	v_cvt_pk_bf16_f32 v115, v120, v121
	v_add_f32_e32 v114, 1.0, v114
	v_rcp_f32_e32 v125, v114
	v_cvt_pk_bf16_f32 v114, v118, v119
	v_pk_mul_f32 v[124:125], v[116:117], v[124:125]
	v_cvt_pk_bf16_f32 v116, v122, v123
	v_cvt_pk_bf16_f32 v117, v124, v125
	global_store_dwordx4 v140, v[114:117], s[40:41] offset:256 nt
	s_nop 1
	v_mul_f32_e32 v115, 0x3d372713, v106
	v_mul_f32_e32 v115, v106, v115
	v_fma_f32 v115, v106, v115, v106
	v_mul_f32_e32 v115, 0x3f4c422a, v115
	v_add_f32_e32 v115, v115, v115
	v_mul_f32_e32 v115, 0xbfb8aa3b, v115
	v_exp_f32_e32 v115, v115
	v_mul_f32_e32 v114, 0x3d372713, v110
	v_mul_f32_e32 v114, v110, v114
	v_fma_f32 v114, v110, v114, v110
	v_add_f32_e32 v115, 1.0, v115
	v_rcp_f32_e32 v116, v115
	v_mul_f32_e32 v115, 0x3d372713, v111
	v_mul_f32_e32 v115, v111, v115
	v_fma_f32 v115, v111, v115, v111
	v_mul_f32_e32 v114, 0x3f4c422a, v114
	v_mul_f32_e32 v115, 0x3f4c422a, v115
	v_add_f32_e32 v114, v114, v114
	v_add_f32_e32 v115, v115, v115
	v_mul_f32_e32 v114, 0xbfb8aa3b, v114
	v_mul_f32_e32 v115, 0xbfb8aa3b, v115
	v_exp_f32_e32 v114, v114
	v_exp_f32_e32 v115, v115
	v_add_f32_e32 v114, 1.0, v114
	v_add_f32_e32 v115, 1.0, v115
	v_rcp_f32_e32 v114, v114
	v_rcp_f32_e32 v115, v115
	s_nop 0
	v_pk_mul_f32 v[110:111], v[110:111], v[114:115]
	v_mul_f32_e32 v114, 0x3d372713, v107
	v_mul_f32_e32 v114, v107, v114
	v_fma_f32 v114, v107, v114, v107
	v_mul_f32_e32 v114, 0x3f4c422a, v114
	v_add_f32_e32 v114, v114, v114
	v_mul_f32_e32 v114, 0xbfb8aa3b, v114
	v_exp_f32_e32 v114, v114
	s_nop 0
	v_add_f32_e32 v114, 1.0, v114
	v_rcp_f32_e32 v117, v114
	s_nop 0
	v_pk_mul_f32 v[114:115], v[106:107], v[116:117]
	v_mul_f32_e32 v107, 0x3d372713, v108
	v_mul_f32_e32 v107, v108, v107
	v_fma_f32 v107, v108, v107, v108
	v_mul_f32_e32 v107, 0x3f4c422a, v107
	v_add_f32_e32 v107, v107, v107
	v_mul_f32_e32 v107, 0xbfb8aa3b, v107
	v_exp_f32_e32 v107, v107
	v_mul_f32_e32 v106, 0x3d372713, v112
	v_mul_f32_e32 v106, v112, v106
	v_fma_f32 v106, v112, v106, v112
	v_add_f32_e32 v107, 1.0, v107
	v_rcp_f32_e32 v116, v107
	v_mul_f32_e32 v107, 0x3d372713, v113
	v_mul_f32_e32 v107, v113, v107
	v_fma_f32 v107, v113, v107, v113
	v_mul_f32_e32 v106, 0x3f4c422a, v106
	v_mul_f32_e32 v107, 0x3f4c422a, v107
	v_add_f32_e32 v106, v106, v106
	v_add_f32_e32 v107, v107, v107
	v_mul_f32_e32 v106, 0xbfb8aa3b, v106
	v_mul_f32_e32 v107, 0xbfb8aa3b, v107
	v_exp_f32_e32 v106, v106
	v_exp_f32_e32 v107, v107
	v_add_f32_e32 v106, 1.0, v106
	v_add_f32_e32 v107, 1.0, v107
	v_rcp_f32_e32 v106, v106
	v_rcp_f32_e32 v107, v107
	s_nop 0
	v_pk_mul_f32 v[112:113], v[112:113], v[106:107]
	v_mul_f32_e32 v106, 0x3d372713, v109
	v_mul_f32_e32 v106, v109, v106
	v_fma_f32 v106, v109, v106, v109
	v_mul_f32_e32 v106, 0x3f4c422a, v106
	v_add_f32_e32 v106, v106, v106
	v_mul_f32_e32 v106, 0xbfb8aa3b, v106
	v_exp_f32_e32 v106, v106
	v_cvt_pk_bf16_f32 v107, v112, v113
	v_add_f32_e32 v106, 1.0, v106
	v_rcp_f32_e32 v117, v106
	v_cvt_pk_bf16_f32 v106, v110, v111
	v_or_b32_e32 v110, 0x8000, v140
	v_pk_mul_f32 v[116:117], v[108:109], v[116:117]
	v_cvt_pk_bf16_f32 v108, v114, v115
	v_cvt_pk_bf16_f32 v109, v116, v117
	global_store_dwordx4 v110, v[106:109], s[40:41] nt
	s_nop 1
	v_mul_f32_e32 v107, 0x3d372713, v98
	v_mul_f32_e32 v107, v98, v107
	v_fma_f32 v107, v98, v107, v98
	v_mul_f32_e32 v107, 0x3f4c422a, v107
	v_add_f32_e32 v107, v107, v107
	v_mul_f32_e32 v107, 0xbfb8aa3b, v107
	v_exp_f32_e32 v107, v107
	v_mul_f32_e32 v106, 0x3d372713, v102
	v_mul_f32_e32 v106, v102, v106
	v_fma_f32 v106, v102, v106, v102
	v_add_f32_e32 v107, 1.0, v107
	v_rcp_f32_e32 v108, v107
	v_mul_f32_e32 v107, 0x3d372713, v103
	v_mul_f32_e32 v107, v103, v107
	v_fma_f32 v107, v103, v107, v103
	v_mul_f32_e32 v106, 0x3f4c422a, v106
	v_mul_f32_e32 v107, 0x3f4c422a, v107
	v_add_f32_e32 v106, v106, v106
	v_add_f32_e32 v107, v107, v107
	v_mul_f32_e32 v106, 0xbfb8aa3b, v106
	v_mul_f32_e32 v107, 0xbfb8aa3b, v107
	v_exp_f32_e32 v106, v106
	v_exp_f32_e32 v107, v107
; __device__ __forceinline__ float gelu_tanh_f(float x) { const float z = 0.7978845608028654f * (x + 0.044715f * x * x * x); return x * sigmoid_f(2.0f * z); }
; __device__ __forceinline__ u32x4 pack8(const f32x4 a, const f32x4 b) { u32x4 w; w.x = cvt_pk_rtz(a[0], a[1]); w.y = cvt_pk_rtz(a[2], a[3]); w.z = cvt_pk_rtz(b[0], b[1]); w.w = cvt_pk_rtz(b[2], b[3]); return w; }
; template <class T> __device__ __forceinline__ T* at(const void* base, unsigned byteoff) { return (T*)((char*)base + byteoff); }
;     __device__ __forceinline__ void operator()(const Acc& acc, const pg8::Unit& u, int wr, int wc, int fr, int fq, LAS float* rcache, int& cached_pm) const {
;     ...
;         if (pn < 4) {
;             bf16_t* base = gate + pn * 256;
; #pragma unroll
;             for (int ai = 0; ai < 2; ++ai)
; #pragma unroll
;                 for (int m = 0; m < 4; ++m) {
;                     const int row = row0 + ai * 128 + m * 16; const float rs = rs8[ai * 4 + m];
; #pragma unroll
;                     for (int bj = 0; bj < 2; ++bj) {
;                         f32x4 v0 = acc[ai][bj][m][0] * rs, v1 = acc[ai][bj][m][1] * rs;
; #pragma unroll
;                         for (int j = 0; j < 4; ++j) { v0[j] = gelu_tanh_f(v0[j]); v1[j] = gelu_tanh_f(v1[j]); }
;                         *at<u32x4>(base, (unsigned)(row * DM + bj * 128 + cl) * 2u) = pack8(v0, v1);
;                     }
;                 }
	v_add_f32_e32 v106, 1.0, v106
	v_add_f32_e32 v107, 1.0, v107
	v_rcp_f32_e32 v106, v106
	v_rcp_f32_e32 v107, v107
	s_nop 0
	v_pk_mul_f32 v[102:103], v[102:103], v[106:107]
	v_mul_f32_e32 v106, 0x3d372713, v99
	v_mul_f32_e32 v106, v99, v106
	v_fma_f32 v106, v99, v106, v99
	v_mul_f32_e32 v106, 0x3f4c422a, v106
	v_add_f32_e32 v106, v106, v106
	v_mul_f32_e32 v106, 0xbfb8aa3b, v106
	v_exp_f32_e32 v106, v106
	s_nop 0
	v_add_f32_e32 v106, 1.0, v106
	v_rcp_f32_e32 v109, v106
	s_nop 0
	v_pk_mul_f32 v[106:107], v[98:99], v[108:109]
	v_mul_f32_e32 v99, 0x3d372713, v100
	v_mul_f32_e32 v99, v100, v99
	v_fma_f32 v99, v100, v99, v100
	v_mul_f32_e32 v99, 0x3f4c422a, v99
	v_add_f32_e32 v99, v99, v99
	v_mul_f32_e32 v99, 0xbfb8aa3b, v99
	v_exp_f32_e32 v99, v99
	v_mul_f32_e32 v98, 0x3d372713, v104
	v_mul_f32_e32 v98, v104, v98
	v_fma_f32 v98, v104, v98, v104
	v_add_f32_e32 v99, 1.0, v99
	v_rcp_f32_e32 v108, v99
	v_mul_f32_e32 v99, 0x3d372713, v105
	v_mul_f32_e32 v99, v105, v99
	v_fma_f32 v99, v105, v99, v105
	v_mul_f32_e32 v98, 0x3f4c422a, v98
	v_mul_f32_e32 v99, 0x3f4c422a, v99
	v_add_f32_e32 v98, v98, v98
	v_add_f32_e32 v99, v99, v99
	v_mul_f32_e32 v98, 0xbfb8aa3b, v98
	v_mul_f32_e32 v99, 0xbfb8aa3b, v99
	v_exp_f32_e32 v98, v98
	v_exp_f32_e32 v99, v99
	v_add_f32_e32 v98, 1.0, v98
	v_add_f32_e32 v99, 1.0, v99
	v_rcp_f32_e32 v98, v98
	v_rcp_f32_e32 v99, v99
	s_nop 0
	v_pk_mul_f32 v[104:105], v[104:105], v[98:99]
	v_mul_f32_e32 v98, 0x3d372713, v101
	v_mul_f32_e32 v98, v101, v98
	v_fma_f32 v98, v101, v98, v101
	v_mul_f32_e32 v98, 0x3f4c422a, v98
	v_add_f32_e32 v98, v98, v98
	v_mul_f32_e32 v98, 0xbfb8aa3b, v98
	v_exp_f32_e32 v98, v98
	v_cvt_pk_bf16_f32 v99, v104, v105
	v_add_f32_e32 v98, 1.0, v98
	v_rcp_f32_e32 v109, v98
	v_cvt_pk_bf16_f32 v98, v102, v103
	v_or_b32_e32 v102, 0x8100, v140
	v_pk_mul_f32 v[108:109], v[100:101], v[108:109]
	v_cvt_pk_bf16_f32 v100, v106, v107
	v_cvt_pk_bf16_f32 v101, v108, v109
	global_store_dwordx4 v102, v[98:101], s[40:41] nt
	s_nop 1
	v_mul_f32_e32 v99, 0x3d372713, v90
	v_mul_f32_e32 v99, v90, v99
	v_fma_f32 v99, v90, v99, v90
	v_mul_f32_e32 v99, 0x3f4c422a, v99
	v_add_f32_e32 v99, v99, v99
	v_mul_f32_e32 v99, 0xbfb8aa3b, v99
	v_exp_f32_e32 v99, v99
	v_mul_f32_e32 v98, 0x3d372713, v94
	v_mul_f32_e32 v98, v94, v98
	v_fma_f32 v98, v94, v98, v94
	v_add_f32_e32 v99, 1.0, v99
	v_rcp_f32_e32 v100, v99
	v_mul_f32_e32 v99, 0x3d372713, v95
	v_mul_f32_e32 v99, v95, v99
	v_fma_f32 v99, v95, v99, v95
	v_mul_f32_e32 v98, 0x3f4c422a, v98
	v_mul_f32_e32 v99, 0x3f4c422a, v99
	v_add_f32_e32 v98, v98, v98
	v_add_f32_e32 v99, v99, v99
	v_mul_f32_e32 v98, 0xbfb8aa3b, v98
	v_mul_f32_e32 v99, 0xbfb8aa3b, v99
	v_exp_f32_e32 v98, v98
	v_exp_f32_e32 v99, v99
	v_add_f32_e32 v98, 1.0, v98
	v_add_f32_e32 v99, 1.0, v99
	v_rcp_f32_e32 v98, v98
	v_rcp_f32_e32 v99, v99
	s_nop 0
	v_pk_mul_f32 v[94:95], v[94:95], v[98:99]
	v_mul_f32_e32 v98, 0x3d372713, v91
	v_mul_f32_e32 v98, v91, v98
	v_fma_f32 v98, v91, v98, v91
	v_mul_f32_e32 v98, 0x3f4c422a, v98
	v_add_f32_e32 v98, v98, v98
	v_mul_f32_e32 v98, 0xbfb8aa3b, v98
	v_exp_f32_e32 v98, v98
	s_nop 0
	v_add_f32_e32 v98, 1.0, v98
	v_rcp_f32_e32 v101, v98
	s_nop 0
	v_pk_mul_f32 v[98:99], v[90:91], v[100:101]
	v_mul_f32_e32 v91, 0x3d372713, v92
	v_mul_f32_e32 v91, v92, v91
	v_fma_f32 v91, v92, v91, v92
	v_mul_f32_e32 v91, 0x3f4c422a, v91
	v_add_f32_e32 v91, v91, v91
	v_mul_f32_e32 v91, 0xbfb8aa3b, v91
	v_exp_f32_e32 v91, v91
	v_mul_f32_e32 v90, 0x3d372713, v96
	v_mul_f32_e32 v90, v96, v90
	v_fma_f32 v90, v96, v90, v96
	v_add_f32_e32 v91, 1.0, v91
	v_rcp_f32_e32 v100, v91
	v_mul_f32_e32 v91, 0x3d372713, v97
	v_mul_f32_e32 v91, v97, v91
	v_fma_f32 v91, v97, v91, v97
	v_mul_f32_e32 v90, 0x3f4c422a, v90
	v_mul_f32_e32 v91, 0x3f4c422a, v91
	v_add_f32_e32 v90, v90, v90
	v_add_f32_e32 v91, v91, v91
	v_mul_f32_e32 v90, 0xbfb8aa3b, v90
	v_mul_f32_e32 v91, 0xbfb8aa3b, v91
	v_exp_f32_e32 v90, v90
	v_exp_f32_e32 v91, v91
	v_add_f32_e32 v90, 1.0, v90
	v_add_f32_e32 v91, 1.0, v91
	v_rcp_f32_e32 v90, v90
	v_rcp_f32_e32 v91, v91
	s_nop 0
	v_pk_mul_f32 v[96:97], v[96:97], v[90:91]
	v_mul_f32_e32 v90, 0x3d372713, v93
	v_mul_f32_e32 v90, v93, v90
	v_fma_f32 v90, v93, v90, v93
	v_mul_f32_e32 v90, 0x3f4c422a, v90
	v_add_f32_e32 v90, v90, v90
	v_mul_f32_e32 v90, 0xbfb8aa3b, v90
	v_exp_f32_e32 v90, v90
	v_cvt_pk_bf16_f32 v91, v96, v97
	v_add_f32_e32 v90, 1.0, v90
	v_rcp_f32_e32 v101, v90
	v_cvt_pk_bf16_f32 v90, v94, v95
	v_or_b32_e32 v94, 0x10000, v140
	v_pk_mul_f32 v[100:101], v[92:93], v[100:101]
	v_cvt_pk_bf16_f32 v92, v98, v99
	v_cvt_pk_bf16_f32 v93, v100, v101
	global_store_dwordx4 v94, v[90:93], s[40:41] nt
	s_nop 1
	v_mul_f32_e32 v91, 0x3d372713, v82
	v_mul_f32_e32 v91, v82, v91
	v_fma_f32 v91, v82, v91, v82
	v_mul_f32_e32 v91, 0x3f4c422a, v91
	v_add_f32_e32 v91, v91, v91
	v_mul_f32_e32 v91, 0xbfb8aa3b, v91
	v_exp_f32_e32 v91, v91
	v_mul_f32_e32 v90, 0x3d372713, v86
	v_mul_f32_e32 v90, v86, v90
	v_fma_f32 v90, v86, v90, v86
	v_add_f32_e32 v91, 1.0, v91
	v_rcp_f32_e32 v92, v91
	v_mul_f32_e32 v91, 0x3d372713, v87
	v_mul_f32_e32 v91, v87, v91
	v_fma_f32 v91, v87, v91, v87
	v_mul_f32_e32 v90, 0x3f4c422a, v90
	v_mul_f32_e32 v91, 0x3f4c422a, v91
	v_add_f32_e32 v90, v90, v90
	v_add_f32_e32 v91, v91, v91
	v_mul_f32_e32 v90, 0xbfb8aa3b, v90
	v_mul_f32_e32 v91, 0xbfb8aa3b, v91
	v_exp_f32_e32 v90, v90
	v_exp_f32_e32 v91, v91
	v_add_f32_e32 v90, 1.0, v90
	v_add_f32_e32 v91, 1.0, v91
	v_rcp_f32_e32 v90, v90
	v_rcp_f32_e32 v91, v91
	s_nop 0
	v_pk_mul_f32 v[86:87], v[86:87], v[90:91]
	v_mul_f32_e32 v90, 0x3d372713, v83
	v_mul_f32_e32 v90, v83, v90
	v_fma_f32 v90, v83, v90, v83
	v_mul_f32_e32 v90, 0x3f4c422a, v90
	v_add_f32_e32 v90, v90, v90
; __device__ __forceinline__ float gelu_tanh_f(float x) { const float z = 0.7978845608028654f * (x + 0.044715f * x * x * x); return x * sigmoid_f(2.0f * z); }
; __device__ __forceinline__ u32x4 pack8(const f32x4 a, const f32x4 b) { u32x4 w; w.x = cvt_pk_rtz(a[0], a[1]); w.y = cvt_pk_rtz(a[2], a[3]); w.z = cvt_pk_rtz(b[0], b[1]); w.w = cvt_pk_rtz(b[2], b[3]); return w; }
; template <class T> __device__ __forceinline__ T* at(const void* base, unsigned byteoff) { return (T*)((char*)base + byteoff); }
;     __device__ __forceinline__ void operator()(const Acc& acc, const pg8::Unit& u, int wr, int wc, int fr, int fq, LAS float* rcache, int& cached_pm) const {
;     ...
;         if (pn < 4) {
;             bf16_t* base = gate + pn * 256;
; #pragma unroll
;             for (int ai = 0; ai < 2; ++ai)
; #pragma unroll
;                 for (int m = 0; m < 4; ++m) {
;                     const int row = row0 + ai * 128 + m * 16; const float rs = rs8[ai * 4 + m];
; #pragma unroll
;                     for (int bj = 0; bj < 2; ++bj) {
;                         f32x4 v0 = acc[ai][bj][m][0] * rs, v1 = acc[ai][bj][m][1] * rs;
; #pragma unroll
;                         for (int j = 0; j < 4; ++j) { v0[j] = gelu_tanh_f(v0[j]); v1[j] = gelu_tanh_f(v1[j]); }
;                         *at<u32x4>(base, (unsigned)(row * DM + bj * 128 + cl) * 2u) = pack8(v0, v1);
;                     }
;                 }
	v_mul_f32_e32 v90, 0xbfb8aa3b, v90
	v_exp_f32_e32 v90, v90
	s_nop 0
	v_add_f32_e32 v90, 1.0, v90
	v_rcp_f32_e32 v93, v90
	s_nop 0
	v_pk_mul_f32 v[90:91], v[82:83], v[92:93]
	v_mul_f32_e32 v83, 0x3d372713, v84
	v_mul_f32_e32 v83, v84, v83
	v_fma_f32 v83, v84, v83, v84
	v_mul_f32_e32 v83, 0x3f4c422a, v83
	v_add_f32_e32 v83, v83, v83
	v_mul_f32_e32 v83, 0xbfb8aa3b, v83
	v_exp_f32_e32 v83, v83
	v_mul_f32_e32 v82, 0x3d372713, v88
	v_mul_f32_e32 v82, v88, v82
	v_fma_f32 v82, v88, v82, v88
	v_add_f32_e32 v83, 1.0, v83
	v_rcp_f32_e32 v92, v83
	v_mul_f32_e32 v83, 0x3d372713, v89
	v_mul_f32_e32 v83, v89, v83
	v_fma_f32 v83, v89, v83, v89
	v_mul_f32_e32 v82, 0x3f4c422a, v82
	v_mul_f32_e32 v83, 0x3f4c422a, v83
	v_add_f32_e32 v82, v82, v82
	v_add_f32_e32 v83, v83, v83
	v_mul_f32_e32 v82, 0xbfb8aa3b, v82
	v_mul_f32_e32 v83, 0xbfb8aa3b, v83
	v_exp_f32_e32 v82, v82
	v_exp_f32_e32 v83, v83
	v_add_f32_e32 v82, 1.0, v82
	v_add_f32_e32 v83, 1.0, v83
	v_rcp_f32_e32 v82, v82
	v_rcp_f32_e32 v83, v83
	s_nop 0
	v_pk_mul_f32 v[88:89], v[88:89], v[82:83]
	v_mul_f32_e32 v82, 0x3d372713, v85
	v_mul_f32_e32 v82, v85, v82
	v_fma_f32 v82, v85, v82, v85
	v_mul_f32_e32 v82, 0x3f4c422a, v82
	v_add_f32_e32 v82, v82, v82
	v_mul_f32_e32 v82, 0xbfb8aa3b, v82
	v_exp_f32_e32 v82, v82
	v_cvt_pk_bf16_f32 v83, v88, v89
	v_add_f32_e32 v82, 1.0, v82
	v_rcp_f32_e32 v93, v82
	v_cvt_pk_bf16_f32 v82, v86, v87
	v_or_b32_e32 v86, 0x10100, v140
	v_pk_mul_f32 v[92:93], v[84:85], v[92:93]
	v_cvt_pk_bf16_f32 v84, v90, v91
	v_cvt_pk_bf16_f32 v85, v92, v93
	global_store_dwordx4 v86, v[82:85], s[40:41] nt
	s_nop 1
	v_mov_b32_e32 v82, v159
	v_pk_mul_f32 v[76:77], v[76:77], v[82:83] op_sel_hi:[1,0]
	v_pk_mul_f32 v[78:79], v[78:79], v[82:83] op_sel_hi:[1,0]
	v_pk_mul_f32 v[74:75], v[74:75], v[82:83] op_sel_hi:[1,0]
	v_pk_mul_f32 v[72:73], v[72:73], v[82:83] op_sel_hi:[1,0]
	v_mul_f32_e32 v83, 0x3d372713, v76
	v_mul_f32_e32 v83, v76, v83
	v_fma_f32 v83, v76, v83, v76
	v_mul_f32_e32 v83, 0x3f4c422a, v83
	v_add_f32_e32 v83, v83, v83
	v_mul_f32_e32 v83, 0xbfb8aa3b, v83
	v_exp_f32_e32 v83, v83
	s_nop 0
	v_add_f32_e32 v83, 1.0, v83
	v_rcp_f32_e32 v84, v83
	v_mul_f32_e32 v83, 0x3d372713, v72
	v_mul_f32_e32 v83, v72, v83
	v_fma_f32 v83, v72, v83, v72
	v_mul_f32_e32 v83, 0x3f4c422a, v83
	v_add_f32_e32 v83, v83, v83
	v_mul_f32_e32 v83, 0xbfb8aa3b, v83
	v_exp_f32_e32 v83, v83
	s_nop 0
	v_add_f32_e32 v83, 1.0, v83
	v_rcp_f32_e32 v86, v83
	v_mul_f32_e32 v83, 0x3d372713, v77
	v_mul_f32_e32 v83, v77, v83
	v_fma_f32 v83, v77, v83, v77
	v_mul_f32_e32 v83, 0x3f4c422a, v83
	v_add_f32_e32 v83, v83, v83
	v_mul_f32_e32 v83, 0xbfb8aa3b, v83
	v_exp_f32_e32 v83, v83
	s_nop 0
	v_add_f32_e32 v83, 1.0, v83
	v_rcp_f32_e32 v85, v83
	v_mul_f32_e32 v83, 0x3d372713, v73
	v_mul_f32_e32 v83, v73, v83
	v_fma_f32 v83, v73, v83, v73
	v_mul_f32_e32 v83, 0x3f4c422a, v83
	v_add_f32_e32 v83, v83, v83
	v_mul_f32_e32 v83, 0xbfb8aa3b, v83
	v_exp_f32_e32 v83, v83
	v_pk_mul_f32 v[76:77], v[76:77], v[84:85]
	v_add_f32_e32 v83, 1.0, v83
	v_rcp_f32_e32 v87, v83
	v_pk_mul_f32 v[64:65], v[64:65], v[82:83] op_sel_hi:[1,0]
	v_pk_mul_f32 v[68:69], v[68:69], v[82:83] op_sel_hi:[1,0]
	v_pk_mul_f32 v[66:67], v[66:67], v[82:83] op_sel_hi:[1,0]
	v_pk_mul_f32 v[84:85], v[72:73], v[86:87]
	v_mul_f32_e32 v73, 0x3d372713, v74
	v_mul_f32_e32 v73, v74, v73
	v_fma_f32 v73, v74, v73, v74
	v_mul_f32_e32 v73, 0x3f4c422a, v73
	v_add_f32_e32 v73, v73, v73
	v_mul_f32_e32 v73, 0xbfb8aa3b, v73
	v_exp_f32_e32 v73, v73
	v_mul_f32_e32 v72, 0x3d372713, v78
	v_mul_f32_e32 v72, v78, v72
	v_fma_f32 v72, v78, v72, v78
	v_add_f32_e32 v73, 1.0, v73
	v_rcp_f32_e32 v86, v73
	v_mul_f32_e32 v73, 0x3d372713, v79
	v_mul_f32_e32 v73, v79, v73
	v_fma_f32 v73, v79, v73, v79
	v_mul_f32_e32 v72, 0x3f4c422a, v72
	v_mul_f32_e32 v73, 0x3f4c422a, v73
	v_add_f32_e32 v72, v72, v72
	v_add_f32_e32 v73, v73, v73
	v_mul_f32_e32 v72, 0xbfb8aa3b, v72
	v_mul_f32_e32 v73, 0xbfb8aa3b, v73
	v_exp_f32_e32 v72, v72
	v_exp_f32_e32 v73, v73
	v_pk_mul_f32 v[70:71], v[70:71], v[82:83] op_sel_hi:[1,0]
	v_add_f32_e32 v72, 1.0, v72
	v_add_f32_e32 v73, 1.0, v73
	v_rcp_f32_e32 v72, v72
	v_rcp_f32_e32 v73, v73
	s_nop 0
	v_pk_mul_f32 v[78:79], v[78:79], v[72:73]
	v_mul_f32_e32 v72, 0x3d372713, v75
	v_mul_f32_e32 v72, v75, v72
	v_fma_f32 v72, v75, v72, v75
	v_mul_f32_e32 v72, 0x3f4c422a, v72
	v_add_f32_e32 v72, v72, v72
	v_mul_f32_e32 v72, 0xbfb8aa3b, v72
	v_exp_f32_e32 v72, v72
	v_cvt_pk_bf16_f32 v73, v78, v79
	v_add_f32_e32 v72, 1.0, v72
	v_rcp_f32_e32 v87, v72
	v_cvt_pk_bf16_f32 v72, v76, v77
	v_or_b32_e32 v76, 0x18000, v140
	v_pk_mul_f32 v[86:87], v[74:75], v[86:87]
	v_cvt_pk_bf16_f32 v74, v84, v85
	v_cvt_pk_bf16_f32 v75, v86, v87
	global_store_dwordx4 v76, v[72:75], s[40:41] nt
	s_nop 1
	v_mul_f32_e32 v73, 0x3d372713, v64
	v_mul_f32_e32 v73, v64, v73
	v_fma_f32 v73, v64, v73, v64
	v_mul_f32_e32 v73, 0x3f4c422a, v73
	v_add_f32_e32 v73, v73, v73
	v_mul_f32_e32 v73, 0xbfb8aa3b, v73
	v_exp_f32_e32 v73, v73
	v_mul_f32_e32 v72, 0x3d372713, v68
	v_mul_f32_e32 v72, v68, v72
	v_fma_f32 v72, v68, v72, v68
	v_add_f32_e32 v73, 1.0, v73
	v_rcp_f32_e32 v74, v73
	v_mul_f32_e32 v73, 0x3d372713, v69
	v_mul_f32_e32 v73, v69, v73
	v_fma_f32 v73, v69, v73, v69
	v_mul_f32_e32 v72, 0x3f4c422a, v72
	v_mul_f32_e32 v73, 0x3f4c422a, v73
	v_add_f32_e32 v72, v72, v72
	v_add_f32_e32 v73, v73, v73
	v_mul_f32_e32 v72, 0xbfb8aa3b, v72
	v_mul_f32_e32 v73, 0xbfb8aa3b, v73
	v_exp_f32_e32 v72, v72
	v_exp_f32_e32 v73, v73
	v_add_f32_e32 v72, 1.0, v72
	v_add_f32_e32 v73, 1.0, v73
	v_rcp_f32_e32 v72, v72
	v_rcp_f32_e32 v73, v73
	s_nop 0
	v_pk_mul_f32 v[68:69], v[68:69], v[72:73]
	v_mul_f32_e32 v72, 0x3d372713, v65
	v_mul_f32_e32 v72, v65, v72
; __device__ __forceinline__ float gelu_tanh_f(float x) { const float z = 0.7978845608028654f * (x + 0.044715f * x * x * x); return x * sigmoid_f(2.0f * z); }
; __device__ __forceinline__ u32x4 pack8(const f32x4 a, const f32x4 b) { u32x4 w; w.x = cvt_pk_rtz(a[0], a[1]); w.y = cvt_pk_rtz(a[2], a[3]); w.z = cvt_pk_rtz(b[0], b[1]); w.w = cvt_pk_rtz(b[2], b[3]); return w; }
; template <class T> __device__ __forceinline__ T* at(const void* base, unsigned byteoff) { return (T*)((char*)base + byteoff); }
;     __device__ __forceinline__ void operator()(const Acc& acc, const pg8::Unit& u, int wr, int wc, int fr, int fq, LAS float* rcache, int& cached_pm) const {
;     ...
;         if (pn < 4) {
;             bf16_t* base = gate + pn * 256;
; #pragma unroll
;             for (int ai = 0; ai < 2; ++ai)
; #pragma unroll
;                 for (int m = 0; m < 4; ++m) {
;                     const int row = row0 + ai * 128 + m * 16; const float rs = rs8[ai * 4 + m];
; #pragma unroll
;                     for (int bj = 0; bj < 2; ++bj) {
;                         f32x4 v0 = acc[ai][bj][m][0] * rs, v1 = acc[ai][bj][m][1] * rs;
; #pragma unroll
;                         for (int j = 0; j < 4; ++j) { v0[j] = gelu_tanh_f(v0[j]); v1[j] = gelu_tanh_f(v1[j]); }
;                         *at<u32x4>(base, (unsigned)(row * DM + bj * 128 + cl) * 2u) = pack8(v0, v1);
;                     }
;                 }
	v_fma_f32 v72, v65, v72, v65
	v_mul_f32_e32 v72, 0x3f4c422a, v72
	v_add_f32_e32 v72, v72, v72
	v_mul_f32_e32 v72, 0xbfb8aa3b, v72
	v_exp_f32_e32 v72, v72
	s_nop 0
	v_add_f32_e32 v72, 1.0, v72
	v_rcp_f32_e32 v75, v72
	s_nop 0
	v_pk_mul_f32 v[72:73], v[64:65], v[74:75]
	v_mul_f32_e32 v65, 0x3d372713, v66
	v_mul_f32_e32 v65, v66, v65
	v_fma_f32 v65, v66, v65, v66
	v_mul_f32_e32 v65, 0x3f4c422a, v65
	v_add_f32_e32 v65, v65, v65
	v_mul_f32_e32 v65, 0xbfb8aa3b, v65
	v_exp_f32_e32 v65, v65
	v_mul_f32_e32 v64, 0x3d372713, v70
	v_mul_f32_e32 v64, v70, v64
	v_fma_f32 v64, v70, v64, v70
	v_add_f32_e32 v65, 1.0, v65
	v_rcp_f32_e32 v74, v65
	v_mul_f32_e32 v65, 0x3d372713, v71
	v_mul_f32_e32 v65, v71, v65
	v_fma_f32 v65, v71, v65, v71
	v_mul_f32_e32 v64, 0x3f4c422a, v64
	v_mul_f32_e32 v65, 0x3f4c422a, v65
	v_add_f32_e32 v64, v64, v64
	v_add_f32_e32 v65, v65, v65
	v_mul_f32_e32 v64, 0xbfb8aa3b, v64
	v_mul_f32_e32 v65, 0xbfb8aa3b, v65
	v_exp_f32_e32 v64, v64
	v_exp_f32_e32 v65, v65
	v_add_f32_e32 v64, 1.0, v64
	v_add_f32_e32 v65, 1.0, v65
	v_rcp_f32_e32 v64, v64
	v_rcp_f32_e32 v65, v65
	s_nop 0
	v_pk_mul_f32 v[70:71], v[70:71], v[64:65]
	v_mul_f32_e32 v64, 0x3d372713, v67
	v_mul_f32_e32 v64, v67, v64
	v_fma_f32 v64, v67, v64, v67
	v_mul_f32_e32 v64, 0x3f4c422a, v64
	v_add_f32_e32 v64, v64, v64
	v_mul_f32_e32 v64, 0xbfb8aa3b, v64
	v_exp_f32_e32 v64, v64
	v_cvt_pk_bf16_f32 v65, v70, v71
	v_add_f32_e32 v64, 1.0, v64
	v_rcp_f32_e32 v75, v64
	v_cvt_pk_bf16_f32 v64, v68, v69
	v_or_b32_e32 v68, 0x18100, v140
	v_pk_mul_f32 v[74:75], v[66:67], v[74:75]
	v_cvt_pk_bf16_f32 v66, v72, v73
	v_cvt_pk_bf16_f32 v67, v74, v75
	global_store_dwordx4 v68, v[64:67], s[40:41] nt
	s_nop 1
	v_mul_f32_e32 v65, 0x3d372713, v56
	v_mul_f32_e32 v65, v56, v65
	v_fma_f32 v65, v56, v65, v56
	v_mul_f32_e32 v65, 0x3f4c422a, v65
	v_add_f32_e32 v65, v65, v65
	v_mul_f32_e32 v65, 0xbfb8aa3b, v65
	v_exp_f32_e32 v65, v65
	v_mul_f32_e32 v64, 0x3d372713, v60
	v_mul_f32_e32 v64, v60, v64
	v_fma_f32 v64, v60, v64, v60
	v_add_f32_e32 v65, 1.0, v65
	v_rcp_f32_e32 v66, v65
	v_mul_f32_e32 v65, 0x3d372713, v61
	v_mul_f32_e32 v65, v61, v65
	v_fma_f32 v65, v61, v65, v61
	v_mul_f32_e32 v64, 0x3f4c422a, v64
	v_mul_f32_e32 v65, 0x3f4c422a, v65
	v_add_f32_e32 v64, v64, v64
	v_add_f32_e32 v65, v65, v65
	v_mul_f32_e32 v64, 0xbfb8aa3b, v64
	v_mul_f32_e32 v65, 0xbfb8aa3b, v65
	v_exp_f32_e32 v64, v64
	v_exp_f32_e32 v65, v65
	v_add_f32_e32 v64, 1.0, v64
	v_add_f32_e32 v65, 1.0, v65
	v_rcp_f32_e32 v64, v64
	v_rcp_f32_e32 v65, v65
	s_nop 0
	v_pk_mul_f32 v[60:61], v[60:61], v[64:65]
	v_mul_f32_e32 v64, 0x3d372713, v57
	v_mul_f32_e32 v64, v57, v64
	v_fma_f32 v64, v57, v64, v57
	v_mul_f32_e32 v64, 0x3f4c422a, v64
	v_add_f32_e32 v64, v64, v64
	v_mul_f32_e32 v64, 0xbfb8aa3b, v64
	v_exp_f32_e32 v64, v64
	s_nop 0
	v_add_f32_e32 v64, 1.0, v64
	v_rcp_f32_e32 v67, v64
	s_nop 0
	v_pk_mul_f32 v[64:65], v[56:57], v[66:67]
	v_mul_f32_e32 v57, 0x3d372713, v58
	v_mul_f32_e32 v57, v58, v57
	v_fma_f32 v57, v58, v57, v58
	v_mul_f32_e32 v57, 0x3f4c422a, v57
	v_add_f32_e32 v57, v57, v57
	v_mul_f32_e32 v57, 0xbfb8aa3b, v57
	v_exp_f32_e32 v57, v57
	v_mul_f32_e32 v56, 0x3d372713, v62
	v_mul_f32_e32 v56, v62, v56
	v_fma_f32 v56, v62, v56, v62
	v_add_f32_e32 v57, 1.0, v57
	v_rcp_f32_e32 v66, v57
	v_mul_f32_e32 v57, 0x3d372713, v63
	v_mul_f32_e32 v57, v63, v57
	v_fma_f32 v57, v63, v57, v63
	v_mul_f32_e32 v56, 0x3f4c422a, v56
	v_mul_f32_e32 v57, 0x3f4c422a, v57
	v_add_f32_e32 v56, v56, v56
	v_add_f32_e32 v57, v57, v57
	v_mul_f32_e32 v56, 0xbfb8aa3b, v56
	v_mul_f32_e32 v57, 0xbfb8aa3b, v57
	v_exp_f32_e32 v56, v56
	v_exp_f32_e32 v57, v57
	v_add_f32_e32 v56, 1.0, v56
	v_add_f32_e32 v57, 1.0, v57
	v_rcp_f32_e32 v56, v56
	v_rcp_f32_e32 v57, v57
	s_nop 0
	v_pk_mul_f32 v[62:63], v[62:63], v[56:57]
	v_mul_f32_e32 v56, 0x3d372713, v59
	v_mul_f32_e32 v56, v59, v56
	v_fma_f32 v56, v59, v56, v59
	v_mul_f32_e32 v56, 0x3f4c422a, v56
	v_add_f32_e32 v56, v56, v56
	v_mul_f32_e32 v56, 0xbfb8aa3b, v56
	v_exp_f32_e32 v56, v56
	v_cvt_pk_bf16_f32 v57, v62, v63
	v_add_f32_e32 v56, 1.0, v56
	v_rcp_f32_e32 v67, v56
	v_cvt_pk_bf16_f32 v56, v60, v61
	v_add_u32_e32 v60, 0x40000, v140
	v_pk_mul_f32 v[66:67], v[58:59], v[66:67]
	v_cvt_pk_bf16_f32 v58, v64, v65
	v_cvt_pk_bf16_f32 v59, v66, v67
	global_store_dwordx4 v60, v[56:59], s[40:41] nt
	s_nop 1
	v_mul_f32_e32 v57, 0x3d372713, v48
	v_mul_f32_e32 v57, v48, v57
	v_fma_f32 v57, v48, v57, v48
	v_mul_f32_e32 v57, 0x3f4c422a, v57
	v_add_f32_e32 v57, v57, v57
	v_mul_f32_e32 v57, 0xbfb8aa3b, v57
	v_exp_f32_e32 v57, v57
	v_mul_f32_e32 v56, 0x3d372713, v52
	v_mul_f32_e32 v56, v52, v56
	v_fma_f32 v56, v52, v56, v52
	v_add_f32_e32 v57, 1.0, v57
	v_rcp_f32_e32 v58, v57
	v_mul_f32_e32 v57, 0x3d372713, v53
	v_mul_f32_e32 v57, v53, v57
	v_fma_f32 v57, v53, v57, v53
	v_mul_f32_e32 v56, 0x3f4c422a, v56
	v_mul_f32_e32 v57, 0x3f4c422a, v57
	v_add_f32_e32 v56, v56, v56
	v_add_f32_e32 v57, v57, v57
	v_mul_f32_e32 v56, 0xbfb8aa3b, v56
	v_mul_f32_e32 v57, 0xbfb8aa3b, v57
	v_exp_f32_e32 v56, v56
	v_exp_f32_e32 v57, v57
	v_add_f32_e32 v56, 1.0, v56
	v_add_f32_e32 v57, 1.0, v57
	v_rcp_f32_e32 v56, v56
	v_rcp_f32_e32 v57, v57
	s_nop 0
	v_pk_mul_f32 v[52:53], v[52:53], v[56:57]
	v_mul_f32_e32 v56, 0x3d372713, v49
	v_mul_f32_e32 v56, v49, v56
	v_fma_f32 v56, v49, v56, v49
	v_mul_f32_e32 v56, 0x3f4c422a, v56
	v_add_f32_e32 v56, v56, v56
	v_mul_f32_e32 v56, 0xbfb8aa3b, v56
	v_exp_f32_e32 v56, v56
	s_nop 0
	v_add_f32_e32 v56, 1.0, v56
	v_rcp_f32_e32 v59, v56
	s_nop 0
	v_pk_mul_f32 v[56:57], v[48:49], v[58:59]
	v_mul_f32_e32 v49, 0x3d372713, v50
	v_mul_f32_e32 v49, v50, v49
	v_fma_f32 v49, v50, v49, v50
	v_mul_f32_e32 v49, 0x3f4c422a, v49
; __device__ __forceinline__ float gelu_tanh_f(float x) { const float z = 0.7978845608028654f * (x + 0.044715f * x * x * x); return x * sigmoid_f(2.0f * z); }
; __device__ __forceinline__ u32x4 pack8(const f32x4 a, const f32x4 b) { u32x4 w; w.x = cvt_pk_rtz(a[0], a[1]); w.y = cvt_pk_rtz(a[2], a[3]); w.z = cvt_pk_rtz(b[0], b[1]); w.w = cvt_pk_rtz(b[2], b[3]); return w; }
; template <class T> __device__ __forceinline__ T* at(const void* base, unsigned byteoff) { return (T*)((char*)base + byteoff); }
;     __device__ __forceinline__ void operator()(const Acc& acc, const pg8::Unit& u, int wr, int wc, int fr, int fq, LAS float* rcache, int& cached_pm) const {
;     ...
;         if (pn < 4) {
;             bf16_t* base = gate + pn * 256;
; #pragma unroll
;             for (int ai = 0; ai < 2; ++ai)
; #pragma unroll
;                 for (int m = 0; m < 4; ++m) {
;                     const int row = row0 + ai * 128 + m * 16; const float rs = rs8[ai * 4 + m];
; #pragma unroll
;                     for (int bj = 0; bj < 2; ++bj) {
;                         f32x4 v0 = acc[ai][bj][m][0] * rs, v1 = acc[ai][bj][m][1] * rs;
; #pragma unroll
;                         for (int j = 0; j < 4; ++j) { v0[j] = gelu_tanh_f(v0[j]); v1[j] = gelu_tanh_f(v1[j]); }
;                         *at<u32x4>(base, (unsigned)(row * DM + bj * 128 + cl) * 2u) = pack8(v0, v1);
;                     }
;                 }
	v_add_f32_e32 v49, v49, v49
	v_mul_f32_e32 v49, 0xbfb8aa3b, v49
	v_exp_f32_e32 v49, v49
	v_mul_f32_e32 v48, 0x3d372713, v54
	v_mul_f32_e32 v48, v54, v48
	v_fma_f32 v48, v54, v48, v54
	v_add_f32_e32 v49, 1.0, v49
	v_rcp_f32_e32 v58, v49
	v_mul_f32_e32 v49, 0x3d372713, v55
	v_mul_f32_e32 v49, v55, v49
	v_fma_f32 v49, v55, v49, v55
	v_mul_f32_e32 v48, 0x3f4c422a, v48
	v_mul_f32_e32 v49, 0x3f4c422a, v49
	v_add_f32_e32 v48, v48, v48
	v_add_f32_e32 v49, v49, v49
	v_mul_f32_e32 v48, 0xbfb8aa3b, v48
	v_mul_f32_e32 v49, 0xbfb8aa3b, v49
	v_exp_f32_e32 v48, v48
	v_exp_f32_e32 v49, v49
	v_add_f32_e32 v48, 1.0, v48
	v_add_f32_e32 v49, 1.0, v49
	v_rcp_f32_e32 v48, v48
	v_rcp_f32_e32 v49, v49
	s_nop 0
	v_pk_mul_f32 v[54:55], v[54:55], v[48:49]
	v_mul_f32_e32 v48, 0x3d372713, v51
	v_mul_f32_e32 v48, v51, v48
	v_fma_f32 v48, v51, v48, v51
	v_mul_f32_e32 v48, 0x3f4c422a, v48
	v_add_f32_e32 v48, v48, v48
	v_mul_f32_e32 v48, 0xbfb8aa3b, v48
	v_exp_f32_e32 v48, v48
	v_cvt_pk_bf16_f32 v49, v54, v55
	v_add_f32_e32 v48, 1.0, v48
	v_rcp_f32_e32 v59, v48
	v_cvt_pk_bf16_f32 v48, v52, v53
	v_add_u32_e32 v52, 0x40100, v140
	v_pk_mul_f32 v[58:59], v[50:51], v[58:59]
	v_cvt_pk_bf16_f32 v50, v56, v57
	v_cvt_pk_bf16_f32 v51, v58, v59
	global_store_dwordx4 v52, v[48:51], s[40:41] nt
	s_nop 1
	v_mov_b32_e32 v48, v139
	v_pk_mul_f32 v[44:45], v[44:45], v[48:49] op_sel_hi:[1,0]
	v_pk_mul_f32 v[46:47], v[46:47], v[48:49] op_sel_hi:[1,0]
	v_pk_mul_f32 v[42:43], v[42:43], v[48:49] op_sel_hi:[1,0]
	v_pk_mul_f32 v[40:41], v[40:41], v[48:49] op_sel_hi:[1,0]
	v_mul_f32_e32 v49, 0x3d372713, v44
	v_mul_f32_e32 v49, v44, v49
	v_fma_f32 v49, v44, v49, v44
	v_mul_f32_e32 v49, 0x3f4c422a, v49
	v_add_f32_e32 v49, v49, v49
	v_mul_f32_e32 v49, 0xbfb8aa3b, v49
	v_exp_f32_e32 v49, v49
	s_nop 0
	v_add_f32_e32 v49, 1.0, v49
	v_rcp_f32_e32 v50, v49
	v_mul_f32_e32 v49, 0x3d372713, v40
	v_mul_f32_e32 v49, v40, v49
	v_fma_f32 v49, v40, v49, v40
	v_mul_f32_e32 v49, 0x3f4c422a, v49
	v_add_f32_e32 v49, v49, v49
	v_mul_f32_e32 v49, 0xbfb8aa3b, v49
	v_exp_f32_e32 v49, v49
	s_nop 0
	v_add_f32_e32 v49, 1.0, v49
	v_rcp_f32_e32 v52, v49
	v_mul_f32_e32 v49, 0x3d372713, v45
	v_mul_f32_e32 v49, v45, v49
	v_fma_f32 v49, v45, v49, v45
	v_mul_f32_e32 v49, 0x3f4c422a, v49
	v_add_f32_e32 v49, v49, v49
	v_mul_f32_e32 v49, 0xbfb8aa3b, v49
	v_exp_f32_e32 v49, v49
	s_nop 0
	v_add_f32_e32 v49, 1.0, v49
	v_rcp_f32_e32 v51, v49
	v_mul_f32_e32 v49, 0x3d372713, v41
	v_mul_f32_e32 v49, v41, v49
	v_fma_f32 v49, v41, v49, v41
	v_mul_f32_e32 v49, 0x3f4c422a, v49
	v_add_f32_e32 v49, v49, v49
	v_mul_f32_e32 v49, 0xbfb8aa3b, v49
	v_exp_f32_e32 v49, v49
	v_pk_mul_f32 v[44:45], v[44:45], v[50:51]
	v_add_f32_e32 v49, 1.0, v49
	v_rcp_f32_e32 v53, v49
	v_pk_mul_f32 v[32:33], v[32:33], v[48:49] op_sel_hi:[1,0]
	v_pk_mul_f32 v[36:37], v[36:37], v[48:49] op_sel_hi:[1,0]
	v_pk_mul_f32 v[34:35], v[34:35], v[48:49] op_sel_hi:[1,0]
	v_pk_mul_f32 v[50:51], v[40:41], v[52:53]
	v_mul_f32_e32 v41, 0x3d372713, v42
	v_mul_f32_e32 v41, v42, v41
	v_fma_f32 v41, v42, v41, v42
	v_mul_f32_e32 v41, 0x3f4c422a, v41
	v_add_f32_e32 v41, v41, v41
	v_mul_f32_e32 v41, 0xbfb8aa3b, v41
	v_exp_f32_e32 v41, v41
	v_mul_f32_e32 v40, 0x3d372713, v46
	v_mul_f32_e32 v40, v46, v40
	v_fma_f32 v40, v46, v40, v46
	v_add_f32_e32 v41, 1.0, v41
	v_rcp_f32_e32 v52, v41
	v_mul_f32_e32 v41, 0x3d372713, v47
	v_mul_f32_e32 v41, v47, v41
	v_fma_f32 v41, v47, v41, v47
	v_mul_f32_e32 v40, 0x3f4c422a, v40
	v_mul_f32_e32 v41, 0x3f4c422a, v41
	v_add_f32_e32 v40, v40, v40
	v_add_f32_e32 v41, v41, v41
	v_mul_f32_e32 v40, 0xbfb8aa3b, v40
	v_mul_f32_e32 v41, 0xbfb8aa3b, v41
	v_exp_f32_e32 v40, v40
	v_exp_f32_e32 v41, v41
	v_pk_mul_f32 v[38:39], v[38:39], v[48:49] op_sel_hi:[1,0]
	v_add_f32_e32 v40, 1.0, v40
	v_add_f32_e32 v41, 1.0, v41
	v_rcp_f32_e32 v40, v40
	v_rcp_f32_e32 v41, v41
	s_nop 0
	v_pk_mul_f32 v[46:47], v[46:47], v[40:41]
	v_mul_f32_e32 v40, 0x3d372713, v43
	v_mul_f32_e32 v40, v43, v40
	v_fma_f32 v40, v43, v40, v43
	v_mul_f32_e32 v40, 0x3f4c422a, v40
	v_add_f32_e32 v40, v40, v40
	v_mul_f32_e32 v40, 0xbfb8aa3b, v40
	v_exp_f32_e32 v40, v40
	v_cvt_pk_bf16_f32 v41, v46, v47
	v_add_f32_e32 v40, 1.0, v40
	v_rcp_f32_e32 v53, v40
	v_cvt_pk_bf16_f32 v40, v44, v45
	v_add_u32_e32 v44, 0x48000, v140
	v_pk_mul_f32 v[52:53], v[42:43], v[52:53]
	v_cvt_pk_bf16_f32 v42, v50, v51
	v_cvt_pk_bf16_f32 v43, v52, v53
	global_store_dwordx4 v44, v[40:43], s[40:41] nt
	s_nop 1
	v_mul_f32_e32 v41, 0x3d372713, v32
	v_mul_f32_e32 v41, v32, v41
	v_fma_f32 v41, v32, v41, v32
	v_mul_f32_e32 v41, 0x3f4c422a, v41
	v_add_f32_e32 v41, v41, v41
	v_mul_f32_e32 v41, 0xbfb8aa3b, v41
	v_exp_f32_e32 v41, v41
	v_mul_f32_e32 v40, 0x3d372713, v36
	v_mul_f32_e32 v40, v36, v40
	v_fma_f32 v40, v36, v40, v36
	v_add_f32_e32 v41, 1.0, v41
	v_rcp_f32_e32 v42, v41
	v_mul_f32_e32 v41, 0x3d372713, v37
	v_mul_f32_e32 v41, v37, v41
	v_fma_f32 v41, v37, v41, v37
	v_mul_f32_e32 v40, 0x3f4c422a, v40
	v_mul_f32_e32 v41, 0x3f4c422a, v41
	v_add_f32_e32 v40, v40, v40
	v_add_f32_e32 v41, v41, v41
	v_mul_f32_e32 v40, 0xbfb8aa3b, v40
	v_mul_f32_e32 v41, 0xbfb8aa3b, v41
	v_exp_f32_e32 v40, v40
	v_exp_f32_e32 v41, v41
	v_add_f32_e32 v40, 1.0, v40
	v_add_f32_e32 v41, 1.0, v41
	v_rcp_f32_e32 v40, v40
	v_rcp_f32_e32 v41, v41
	s_nop 0
	v_pk_mul_f32 v[36:37], v[36:37], v[40:41]
	v_mul_f32_e32 v40, 0x3d372713, v33
	v_mul_f32_e32 v40, v33, v40
	v_fma_f32 v40, v33, v40, v33
	v_mul_f32_e32 v40, 0x3f4c422a, v40
	v_add_f32_e32 v40, v40, v40
	v_mul_f32_e32 v40, 0xbfb8aa3b, v40
	v_exp_f32_e32 v40, v40
	s_nop 0
	v_add_f32_e32 v40, 1.0, v40
	v_rcp_f32_e32 v43, v40
	s_nop 0
	v_pk_mul_f32 v[40:41], v[32:33], v[42:43]
	v_mul_f32_e32 v33, 0x3d372713, v34
; __device__ __forceinline__ float gelu_tanh_f(float x) { const float z = 0.7978845608028654f * (x + 0.044715f * x * x * x); return x * sigmoid_f(2.0f * z); }
; __device__ __forceinline__ u32x4 pack8(const f32x4 a, const f32x4 b) { u32x4 w; w.x = cvt_pk_rtz(a[0], a[1]); w.y = cvt_pk_rtz(a[2], a[3]); w.z = cvt_pk_rtz(b[0], b[1]); w.w = cvt_pk_rtz(b[2], b[3]); return w; }
; template <class T> __device__ __forceinline__ T* at(const void* base, unsigned byteoff) { return (T*)((char*)base + byteoff); }
;     __device__ __forceinline__ void operator()(const Acc& acc, const pg8::Unit& u, int wr, int wc, int fr, int fq, LAS float* rcache, int& cached_pm) const {
;     ...
;         if (pn < 4) {
;             bf16_t* base = gate + pn * 256;
; #pragma unroll
;             for (int ai = 0; ai < 2; ++ai)
; #pragma unroll
;                 for (int m = 0; m < 4; ++m) {
;                     const int row = row0 + ai * 128 + m * 16; const float rs = rs8[ai * 4 + m];
; #pragma unroll
;                     for (int bj = 0; bj < 2; ++bj) {
;                         f32x4 v0 = acc[ai][bj][m][0] * rs, v1 = acc[ai][bj][m][1] * rs;
; #pragma unroll
;                         for (int j = 0; j < 4; ++j) { v0[j] = gelu_tanh_f(v0[j]); v1[j] = gelu_tanh_f(v1[j]); }
;                         *at<u32x4>(base, (unsigned)(row * DM + bj * 128 + cl) * 2u) = pack8(v0, v1);
;                     }
;                 }
	v_mul_f32_e32 v33, v34, v33
	v_fma_f32 v33, v34, v33, v34
	v_mul_f32_e32 v33, 0x3f4c422a, v33
	v_add_f32_e32 v33, v33, v33
	v_mul_f32_e32 v33, 0xbfb8aa3b, v33
	v_exp_f32_e32 v33, v33
	v_mul_f32_e32 v32, 0x3d372713, v38
	v_mul_f32_e32 v32, v38, v32
	v_fma_f32 v32, v38, v32, v38
	v_add_f32_e32 v33, 1.0, v33
	v_rcp_f32_e32 v42, v33
	v_mul_f32_e32 v33, 0x3d372713, v39
	v_mul_f32_e32 v33, v39, v33
	v_fma_f32 v33, v39, v33, v39
	v_mul_f32_e32 v32, 0x3f4c422a, v32
	v_mul_f32_e32 v33, 0x3f4c422a, v33
	v_add_f32_e32 v32, v32, v32
	v_add_f32_e32 v33, v33, v33
	v_mul_f32_e32 v32, 0xbfb8aa3b, v32
	v_mul_f32_e32 v33, 0xbfb8aa3b, v33
	v_exp_f32_e32 v32, v32
	v_exp_f32_e32 v33, v33
	v_add_f32_e32 v32, 1.0, v32
	v_add_f32_e32 v33, 1.0, v33
	v_rcp_f32_e32 v32, v32
	v_rcp_f32_e32 v33, v33
	s_nop 0
	v_pk_mul_f32 v[38:39], v[38:39], v[32:33]
	v_mul_f32_e32 v32, 0x3d372713, v35
	v_mul_f32_e32 v32, v35, v32
	v_fma_f32 v32, v35, v32, v35
	v_mul_f32_e32 v32, 0x3f4c422a, v32
	v_add_f32_e32 v32, v32, v32
	v_mul_f32_e32 v32, 0xbfb8aa3b, v32
	v_exp_f32_e32 v32, v32
	v_cvt_pk_bf16_f32 v33, v38, v39
	v_add_f32_e32 v32, 1.0, v32
	v_rcp_f32_e32 v43, v32
	v_cvt_pk_bf16_f32 v32, v36, v37
	v_add_u32_e32 v36, 0x48100, v140
	v_pk_mul_f32 v[42:43], v[34:35], v[42:43]
	v_cvt_pk_bf16_f32 v34, v40, v41
	v_cvt_pk_bf16_f32 v35, v42, v43
	global_store_dwordx4 v36, v[32:35], s[40:41] nt
	s_nop 1
	v_mul_f32_e32 v33, 0x3d372713, v24
	v_mul_f32_e32 v33, v24, v33
	v_fma_f32 v33, v24, v33, v24
	v_mul_f32_e32 v33, 0x3f4c422a, v33
	v_add_f32_e32 v33, v33, v33
	v_mul_f32_e32 v33, 0xbfb8aa3b, v33
	v_exp_f32_e32 v33, v33
	v_mul_f32_e32 v32, 0x3d372713, v28
	v_mul_f32_e32 v32, v28, v32
	v_fma_f32 v32, v28, v32, v28
	v_add_f32_e32 v33, 1.0, v33
	v_rcp_f32_e32 v34, v33
	v_mul_f32_e32 v33, 0x3d372713, v29
	v_mul_f32_e32 v33, v29, v33
	v_fma_f32 v33, v29, v33, v29
	v_mul_f32_e32 v32, 0x3f4c422a, v32
	v_mul_f32_e32 v33, 0x3f4c422a, v33
	v_add_f32_e32 v32, v32, v32
	v_add_f32_e32 v33, v33, v33
	v_mul_f32_e32 v32, 0xbfb8aa3b, v32
	v_mul_f32_e32 v33, 0xbfb8aa3b, v33
	v_exp_f32_e32 v32, v32
	v_exp_f32_e32 v33, v33
	v_add_f32_e32 v32, 1.0, v32
	v_add_f32_e32 v33, 1.0, v33
	v_rcp_f32_e32 v32, v32
	v_rcp_f32_e32 v33, v33
	s_nop 0
	v_pk_mul_f32 v[28:29], v[28:29], v[32:33]
	v_mul_f32_e32 v32, 0x3d372713, v25
	v_mul_f32_e32 v32, v25, v32
	v_fma_f32 v32, v25, v32, v25
	v_mul_f32_e32 v32, 0x3f4c422a, v32
	v_add_f32_e32 v32, v32, v32
	v_mul_f32_e32 v32, 0xbfb8aa3b, v32
	v_exp_f32_e32 v32, v32
	s_nop 0
	v_add_f32_e32 v32, 1.0, v32
	v_rcp_f32_e32 v35, v32
	s_nop 0
	v_pk_mul_f32 v[32:33], v[24:25], v[34:35]
	v_mul_f32_e32 v25, 0x3d372713, v26
	v_mul_f32_e32 v25, v26, v25
	v_fma_f32 v25, v26, v25, v26
	v_mul_f32_e32 v25, 0x3f4c422a, v25
	v_add_f32_e32 v25, v25, v25
	v_mul_f32_e32 v25, 0xbfb8aa3b, v25
	v_exp_f32_e32 v25, v25
	v_mul_f32_e32 v24, 0x3d372713, v30
	v_mul_f32_e32 v24, v30, v24
	v_fma_f32 v24, v30, v24, v30
	v_add_f32_e32 v25, 1.0, v25
	v_rcp_f32_e32 v34, v25
	v_mul_f32_e32 v25, 0x3d372713, v31
	v_mul_f32_e32 v25, v31, v25
	v_fma_f32 v25, v31, v25, v31
	v_mul_f32_e32 v24, 0x3f4c422a, v24
	v_mul_f32_e32 v25, 0x3f4c422a, v25
	v_add_f32_e32 v24, v24, v24
	v_add_f32_e32 v25, v25, v25
	v_mul_f32_e32 v24, 0xbfb8aa3b, v24
	v_mul_f32_e32 v25, 0xbfb8aa3b, v25
	v_exp_f32_e32 v24, v24
	v_exp_f32_e32 v25, v25
	v_add_f32_e32 v24, 1.0, v24
	v_add_f32_e32 v25, 1.0, v25
	v_rcp_f32_e32 v24, v24
	v_rcp_f32_e32 v25, v25
	s_nop 0
	v_pk_mul_f32 v[30:31], v[30:31], v[24:25]
	v_mul_f32_e32 v24, 0x3d372713, v27
	v_mul_f32_e32 v24, v27, v24
	v_fma_f32 v24, v27, v24, v27
	v_mul_f32_e32 v24, 0x3f4c422a, v24
	v_add_f32_e32 v24, v24, v24
	v_mul_f32_e32 v24, 0xbfb8aa3b, v24
	v_exp_f32_e32 v24, v24
	v_cvt_pk_bf16_f32 v25, v30, v31
	v_add_f32_e32 v24, 1.0, v24
	v_rcp_f32_e32 v35, v24
	v_cvt_pk_bf16_f32 v24, v28, v29
	v_add_u32_e32 v28, 0x50000, v140
	v_pk_mul_f32 v[34:35], v[26:27], v[34:35]
	v_cvt_pk_bf16_f32 v26, v32, v33
	v_cvt_pk_bf16_f32 v27, v34, v35
	global_store_dwordx4 v28, v[24:27], s[40:41] nt
	s_nop 1
	v_mul_f32_e32 v25, 0x3d372713, v16
	v_mul_f32_e32 v25, v16, v25
	v_fma_f32 v25, v16, v25, v16
	v_mul_f32_e32 v25, 0x3f4c422a, v25
	v_add_f32_e32 v25, v25, v25
	v_mul_f32_e32 v25, 0xbfb8aa3b, v25
	v_exp_f32_e32 v25, v25
	v_mul_f32_e32 v24, 0x3d372713, v20
	v_mul_f32_e32 v24, v20, v24
	v_fma_f32 v24, v20, v24, v20
	v_add_f32_e32 v25, 1.0, v25
	v_rcp_f32_e32 v26, v25
	v_mul_f32_e32 v25, 0x3d372713, v21
	v_mul_f32_e32 v25, v21, v25
	v_fma_f32 v25, v21, v25, v21
	v_mul_f32_e32 v24, 0x3f4c422a, v24
	v_mul_f32_e32 v25, 0x3f4c422a, v25
	v_add_f32_e32 v24, v24, v24
	v_add_f32_e32 v25, v25, v25
	v_mul_f32_e32 v24, 0xbfb8aa3b, v24
	v_mul_f32_e32 v25, 0xbfb8aa3b, v25
	v_exp_f32_e32 v24, v24
	v_exp_f32_e32 v25, v25
	v_add_f32_e32 v24, 1.0, v24
	v_add_f32_e32 v25, 1.0, v25
	v_rcp_f32_e32 v24, v24
	v_rcp_f32_e32 v25, v25
	s_nop 0
	v_pk_mul_f32 v[20:21], v[20:21], v[24:25]
	v_mul_f32_e32 v24, 0x3d372713, v17
	v_mul_f32_e32 v24, v17, v24
	v_fma_f32 v24, v17, v24, v17
	v_mul_f32_e32 v24, 0x3f4c422a, v24
	v_add_f32_e32 v24, v24, v24
	v_mul_f32_e32 v24, 0xbfb8aa3b, v24
	v_exp_f32_e32 v24, v24
	s_nop 0
	v_add_f32_e32 v24, 1.0, v24
	v_rcp_f32_e32 v27, v24
	s_nop 0
	v_pk_mul_f32 v[24:25], v[16:17], v[26:27]
	v_mul_f32_e32 v17, 0x3d372713, v18
	v_mul_f32_e32 v17, v18, v17
	v_fma_f32 v17, v18, v17, v18
	v_mul_f32_e32 v17, 0x3f4c422a, v17
	v_add_f32_e32 v17, v17, v17
	v_mul_f32_e32 v17, 0xbfb8aa3b, v17
	v_exp_f32_e32 v17, v17
	v_mul_f32_e32 v16, 0x3d372713, v22
	v_mul_f32_e32 v16, v22, v16
	v_fma_f32 v16, v22, v16, v22
	v_add_f32_e32 v17, 1.0, v17
	v_rcp_f32_e32 v26, v17
	v_mul_f32_e32 v17, 0x3d372713, v23
	v_mul_f32_e32 v17, v23, v17
; __device__ __forceinline__ float gelu_tanh_f(float x) { const float z = 0.7978845608028654f * (x + 0.044715f * x * x * x); return x * sigmoid_f(2.0f * z); }
; __device__ __forceinline__ u32x4 pack8(const f32x4 a, const f32x4 b) { u32x4 w; w.x = cvt_pk_rtz(a[0], a[1]); w.y = cvt_pk_rtz(a[2], a[3]); w.z = cvt_pk_rtz(b[0], b[1]); w.w = cvt_pk_rtz(b[2], b[3]); return w; }
; #define PG8_BAR __builtin_amdgcn_s_barrier()
; template <class T> __device__ __forceinline__ T* at(const void* base, unsigned byteoff) { return (T*)((char*)base + byteoff); }
; template <class Epi>
; __device__ __forceinline__ void gemm_phase(LAS unsigned char* lds, const Gemm g, const StaticOrder& S, const Epi& E, int tid_) {
;     ...
;         if (!has_next) break;
; #pragma unroll
;         for (int a = 0; a < 2; ++a)
; #pragma unroll
;             for (int b = 0; b < 2; ++b)
; #pragma unroll
;                 for (int m = 0; m < 4; ++m)
; #pragma unroll
;                     for (int n = 0; n < 2; ++n) acc[a][b][m][n] = (f32x4){0.f, 0.f, 0.f, 0.f};
;         cur = nxt; cA = nA; cB = nB; ++ui;
;         if (wr == 1) PG8_BAR;
;     __device__ __forceinline__ void operator()(const Acc& acc, const pg8::Unit& u, int wr, int wc, int fr, int fq, LAS float* rcache, int& cached_pm) const {
;     ...
;         if (pn < 4) {
;             bf16_t* base = gate + pn * 256;
; #pragma unroll
;             for (int ai = 0; ai < 2; ++ai)
; #pragma unroll
;                 for (int m = 0; m < 4; ++m) {
;                     const int row = row0 + ai * 128 + m * 16; const float rs = rs8[ai * 4 + m];
; #pragma unroll
;                     for (int bj = 0; bj < 2; ++bj) {
;                         f32x4 v0 = acc[ai][bj][m][0] * rs, v1 = acc[ai][bj][m][1] * rs;
; #pragma unroll
;                         for (int j = 0; j < 4; ++j) { v0[j] = gelu_tanh_f(v0[j]); v1[j] = gelu_tanh_f(v1[j]); }
;                         *at<u32x4>(base, (unsigned)(row * DM + bj * 128 + cl) * 2u) = pack8(v0, v1);
;                     }
;                 }
	v_fma_f32 v17, v23, v17, v23
	v_mul_f32_e32 v16, 0x3f4c422a, v16
	v_mul_f32_e32 v17, 0x3f4c422a, v17
	v_add_f32_e32 v16, v16, v16
	v_add_f32_e32 v17, v17, v17
	v_mul_f32_e32 v16, 0xbfb8aa3b, v16
	v_mul_f32_e32 v17, 0xbfb8aa3b, v17
	v_exp_f32_e32 v16, v16
	v_exp_f32_e32 v17, v17
	v_add_f32_e32 v16, 1.0, v16
	v_add_f32_e32 v17, 1.0, v17
	v_rcp_f32_e32 v16, v16
	v_rcp_f32_e32 v17, v17
	s_nop 0
	v_pk_mul_f32 v[22:23], v[22:23], v[16:17]
	v_mul_f32_e32 v16, 0x3d372713, v19
	v_mul_f32_e32 v16, v19, v16
	v_fma_f32 v16, v19, v16, v19
	v_mul_f32_e32 v16, 0x3f4c422a, v16
	v_add_f32_e32 v16, v16, v16
	v_mul_f32_e32 v16, 0xbfb8aa3b, v16
	v_exp_f32_e32 v16, v16
	v_cvt_pk_bf16_f32 v17, v22, v23
	v_add_f32_e32 v16, 1.0, v16
	v_rcp_f32_e32 v27, v16
	v_cvt_pk_bf16_f32 v16, v20, v21
	v_add_u32_e32 v20, 0x50100, v140
	v_pk_mul_f32 v[26:27], v[18:19], v[26:27]
	v_cvt_pk_bf16_f32 v18, v24, v25
	v_cvt_pk_bf16_f32 v19, v26, v27
	global_store_dwordx4 v20, v[16:19], s[40:41] nt
	s_nop 1
	v_mov_b32_e32 v16, v135
	v_pk_mul_f32 v[12:13], v[12:13], v[16:17] op_sel_hi:[1,0]
	v_pk_mul_f32 v[14:15], v[14:15], v[16:17] op_sel_hi:[1,0]
	v_pk_mul_f32 v[10:11], v[10:11], v[16:17] op_sel_hi:[1,0]
	v_pk_mul_f32 v[8:9], v[8:9], v[16:17] op_sel_hi:[1,0]
	v_mul_f32_e32 v17, 0x3d372713, v12
	v_mul_f32_e32 v17, v12, v17
	v_fma_f32 v17, v12, v17, v12
	v_mul_f32_e32 v17, 0x3f4c422a, v17
	v_add_f32_e32 v17, v17, v17
	v_mul_f32_e32 v17, 0xbfb8aa3b, v17
	v_exp_f32_e32 v17, v17
	s_nop 0
	v_add_f32_e32 v17, 1.0, v17
	v_rcp_f32_e32 v18, v17
	v_mul_f32_e32 v17, 0x3d372713, v8
	v_mul_f32_e32 v17, v8, v17
	v_fma_f32 v17, v8, v17, v8
	v_mul_f32_e32 v17, 0x3f4c422a, v17
	v_add_f32_e32 v17, v17, v17
	v_mul_f32_e32 v17, 0xbfb8aa3b, v17
	v_exp_f32_e32 v17, v17
	s_nop 0
	v_add_f32_e32 v17, 1.0, v17
	v_rcp_f32_e32 v20, v17
	v_mul_f32_e32 v17, 0x3d372713, v13
	v_mul_f32_e32 v17, v13, v17
	v_fma_f32 v17, v13, v17, v13
	v_mul_f32_e32 v17, 0x3f4c422a, v17
	v_add_f32_e32 v17, v17, v17
	v_mul_f32_e32 v17, 0xbfb8aa3b, v17
	v_exp_f32_e32 v17, v17
	s_nop 0
	v_add_f32_e32 v17, 1.0, v17
	v_rcp_f32_e32 v19, v17
	v_mul_f32_e32 v17, 0x3d372713, v9
	v_mul_f32_e32 v17, v9, v17
	v_fma_f32 v17, v9, v17, v9
	v_mul_f32_e32 v17, 0x3f4c422a, v17
	v_add_f32_e32 v17, v17, v17
	v_mul_f32_e32 v17, 0xbfb8aa3b, v17
	v_exp_f32_e32 v17, v17
	v_pk_mul_f32 v[12:13], v[12:13], v[18:19]
	v_add_f32_e32 v17, 1.0, v17
	v_rcp_f32_e32 v21, v17
	v_pk_mul_f32 v[0:1], v[0:1], v[16:17] op_sel_hi:[1,0]
	v_pk_mul_f32 v[4:5], v[4:5], v[16:17] op_sel_hi:[1,0]
	v_pk_mul_f32 v[2:3], v[2:3], v[16:17] op_sel_hi:[1,0]
	v_pk_mul_f32 v[18:19], v[8:9], v[20:21]
	v_mul_f32_e32 v9, 0x3d372713, v10
	v_mul_f32_e32 v9, v10, v9
	v_fma_f32 v9, v10, v9, v10
	v_mul_f32_e32 v9, 0x3f4c422a, v9
	v_add_f32_e32 v9, v9, v9
	v_mul_f32_e32 v9, 0xbfb8aa3b, v9
	v_exp_f32_e32 v9, v9
	v_mul_f32_e32 v8, 0x3d372713, v14
	v_mul_f32_e32 v8, v14, v8
	v_fma_f32 v8, v14, v8, v14
	v_add_f32_e32 v9, 1.0, v9
	v_rcp_f32_e32 v20, v9
	v_mul_f32_e32 v9, 0x3d372713, v15
	v_mul_f32_e32 v9, v15, v9
	v_fma_f32 v9, v15, v9, v15
	v_mul_f32_e32 v8, 0x3f4c422a, v8
	v_mul_f32_e32 v9, 0x3f4c422a, v9
	v_add_f32_e32 v8, v8, v8
	v_add_f32_e32 v9, v9, v9
	v_mul_f32_e32 v8, 0xbfb8aa3b, v8
	v_mul_f32_e32 v9, 0xbfb8aa3b, v9
	v_exp_f32_e32 v8, v8
	v_exp_f32_e32 v9, v9
	v_pk_mul_f32 v[6:7], v[6:7], v[16:17] op_sel_hi:[1,0]
	v_add_f32_e32 v8, 1.0, v8
	v_add_f32_e32 v9, 1.0, v9
	v_rcp_f32_e32 v8, v8
	v_rcp_f32_e32 v9, v9
	s_nop 0
	v_pk_mul_f32 v[14:15], v[14:15], v[8:9]
	v_mul_f32_e32 v8, 0x3d372713, v11
	v_mul_f32_e32 v8, v11, v8
	v_fma_f32 v8, v11, v8, v11
	v_mul_f32_e32 v8, 0x3f4c422a, v8
	v_add_f32_e32 v8, v8, v8
	v_mul_f32_e32 v8, 0xbfb8aa3b, v8
	v_exp_f32_e32 v8, v8
	v_cvt_pk_bf16_f32 v9, v14, v15
	v_add_f32_e32 v8, 1.0, v8
	v_rcp_f32_e32 v21, v8
	v_cvt_pk_bf16_f32 v8, v12, v13
	v_add_u32_e32 v12, 0x58000, v140
	v_pk_mul_f32 v[20:21], v[10:11], v[20:21]
	v_cvt_pk_bf16_f32 v10, v18, v19
	v_cvt_pk_bf16_f32 v11, v20, v21
	global_store_dwordx4 v12, v[8:11], s[40:41] nt
	s_nop 1
	v_mul_f32_e32 v9, 0x3d372713, v0
	v_mul_f32_e32 v9, v0, v9
	v_fma_f32 v9, v0, v9, v0
	v_mul_f32_e32 v9, 0x3f4c422a, v9
	v_add_f32_e32 v9, v9, v9
	v_mul_f32_e32 v9, 0xbfb8aa3b, v9
	v_exp_f32_e32 v9, v9
	v_mul_f32_e32 v8, 0x3d372713, v4
	v_mul_f32_e32 v8, v4, v8
	v_fma_f32 v8, v4, v8, v4
	v_add_f32_e32 v9, 1.0, v9
	v_rcp_f32_e32 v10, v9
	v_mul_f32_e32 v9, 0x3d372713, v5
	v_mul_f32_e32 v9, v5, v9
	v_fma_f32 v9, v5, v9, v5
	v_mul_f32_e32 v8, 0x3f4c422a, v8
	v_mul_f32_e32 v9, 0x3f4c422a, v9
	v_add_f32_e32 v8, v8, v8
	v_add_f32_e32 v9, v9, v9
	v_mul_f32_e32 v8, 0xbfb8aa3b, v8
	v_mul_f32_e32 v9, 0xbfb8aa3b, v9
	v_exp_f32_e32 v8, v8
	v_exp_f32_e32 v9, v9
	v_add_f32_e32 v8, 1.0, v8
	v_add_f32_e32 v9, 1.0, v9
	v_rcp_f32_e32 v8, v8
	v_rcp_f32_e32 v9, v9
	s_nop 0
	v_pk_mul_f32 v[4:5], v[4:5], v[8:9]
	v_mul_f32_e32 v8, 0x3d372713, v1
	v_mul_f32_e32 v8, v1, v8
	v_fma_f32 v8, v1, v8, v1
	v_mul_f32_e32 v8, 0x3f4c422a, v8
	v_add_f32_e32 v8, v8, v8
	v_mul_f32_e32 v9, 0x3d372713, v2
	v_mul_f32_e32 v8, 0xbfb8aa3b, v8
	v_mul_f32_e32 v9, v2, v9
	v_exp_f32_e32 v8, v8
	v_fma_f32 v9, v2, v9, v2
	v_mul_f32_e32 v9, 0x3f4c422a, v9
	v_add_f32_e32 v9, v9, v9
	v_mul_f32_e32 v9, 0xbfb8aa3b, v9
	v_add_f32_e32 v8, 1.0, v8
	v_exp_f32_e32 v9, v9
	v_rcp_f32_e32 v11, v8
	v_mul_f32_e32 v8, 0x3d372713, v6
	v_mul_f32_e32 v8, v6, v8
	v_add_f32_e32 v9, 1.0, v9
	v_pk_mul_f32 v[0:1], v[0:1], v[10:11]
	v_rcp_f32_e32 v10, v9
	v_mul_f32_e32 v9, 0x3d372713, v7
	v_mul_f32_e32 v9, v7, v9
	v_fma_f32 v8, v6, v8, v6
	v_fma_f32 v9, v7, v9, v7
	v_mul_f32_e32 v8, 0x3f4c422a, v8
	v_mul_f32_e32 v9, 0x3f4c422a, v9
	v_add_f32_e32 v8, v8, v8
	v_add_f32_e32 v9, v9, v9
	v_mul_f32_e32 v8, 0xbfb8aa3b, v8
	v_mul_f32_e32 v9, 0xbfb8aa3b, v9
	v_exp_f32_e32 v8, v8
	v_exp_f32_e32 v9, v9
	v_cvt_pk_bf16_f32 v130, v4, v5
	v_cvt_pk_bf16_f32 v132, v0, v1
	v_add_f32_e32 v8, 1.0, v8
	v_add_f32_e32 v9, 1.0, v9
	v_rcp_f32_e32 v8, v8
	v_rcp_f32_e32 v9, v9
	s_nop 0
	v_pk_mul_f32 v[6:7], v[6:7], v[8:9]
	v_mul_f32_e32 v8, 0x3d372713, v3
	v_mul_f32_e32 v8, v3, v8
	v_fma_f32 v8, v3, v8, v3
	v_mul_f32_e32 v8, 0x3f4c422a, v8
	v_add_f32_e32 v8, v8, v8
	v_mul_f32_e32 v8, 0xbfb8aa3b, v8
	v_exp_f32_e32 v8, v8
	v_cvt_pk_bf16_f32 v131, v6, v7
	v_add_f32_e32 v8, 1.0, v8
	v_rcp_f32_e32 v11, v8
	s_nop 0
	v_pk_mul_f32 v[136:137], v[2:3], v[10:11]
.LBB0_185:
	s_nop 0
	v_cvt_pk_bf16_f32 v133, v136, v137
	v_add_u32_e32 v0, 0x58100, v141
	s_andn2_b64 vcc, exec, s[38:39]
	s_mov_b64 s[28:29], -1
	global_store_dwordx4 v0, v[130:133], s[40:41] nt
	s_cbranch_vccnz .LBB0_163
	s_andn2_b64 vcc, exec, s[24:25]
	s_cbranch_vccnz .LBB0_162
	s_barrier
	s_branch .LBB0_162
